# v27: v25 with one 16-byte write-through poll load per row instead of four 4-byte loads
# speedup vs baseline: 1.0115x; 1.0115x over previous
;     __device__ __forceinline__ void operator()(const f32x4 (&acc)[2][2][4][2], const Unit& u, int wr, int wc, int fr, int fq) const {
;     ...
;         if (tid < 64) { unsigned sp = 0u;
;             while (__hip_atomic_load(pc, __ATOMIC_RELAXED, __HIP_MEMORY_SCOPE_AGENT) < 4u) { __builtin_amdgcn_s_sleep(2); if (++sp > (1u << 20)) { if (tid == 0) __hip_atomic_store(tmo, 1u, __ATOMIC_RELAXED, __HIP_MEMORY_SCOPE_AGENT); break; } } }
;         asm volatile("s_waitcnt vmcnt(0)" ::: "memory"); __builtin_amdgcn_s_barrier(); asm volatile("" ::: "memory");
;         if (tid < 256) { const float* sp4 = ssq + (size_t)(u.pm * BM + tid) * 4;
;             const float t = (__hip_atomic_load(sp4, __ATOMIC_RELAXED, __HIP_MEMORY_SCOPE_AGENT) + __hip_atomic_load(sp4 + 1, __ATOMIC_RELAXED, __HIP_MEMORY_SCOPE_AGENT))
;                           + (__hip_atomic_load(sp4 + 2, __ATOMIC_RELAXED, __HIP_MEMORY_SCOPE_AGENT) + __hip_atomic_load(sp4 + 3, __ATOMIC_RELAXED, __HIP_MEMORY_SCOPE_AGENT));
;             P[1024 + tid] = 1.f / sqrtf(t * (1.f / DM) + EPS); }
.Lx7_poll:
	global_load_dwordx4 v[150:153], v[146:147], off sc1
	s_waitcnt vmcnt(0)
	v_or3_b32 v149, v150, v151, v152
	v_or_b32_e32 v149, v149, v153
	v_cmp_gt_i32_e32 vcc, 0, v149
	s_cbranch_vccz .Lx7_ready
	s_sleep 1
	s_add_i32 s24, s24, -1
	s_cmp_lg_u32 s24, 0
	s_cbranch_scc1 .Lx7_poll
.Lx7_ready:
	v_swap_b32 v151, v152
	s_mov_b32 s8, 0xf800000
	s_waitcnt vmcnt(0)
	v_pk_add_f32 v[146:147], v[150:151], v[152:153]
	s_nop 0
	v_add_f32_e32 v146, v146, v147
	v_fmamk_f32 v146, v146, 0x3a800000, v233
	v_mul_f32_e32 v147, 0x4f800000, v146
	v_cmp_gt_f32_e32 vcc, s8, v146
	s_nop 1
	v_cndmask_b32_e32 v146, v146, v147, vcc
	v_sqrt_f32_e32 v147, v146
	s_nop 0
	v_add_u32_e32 v149, -1, v147
	v_add_u32_e32 v150, 1, v147
	v_fma_f32 v151, -v149, v147, v146
	v_fma_f32 v152, -v150, v147, v146
	v_cmp_ge_f32_e64 s[12:13], 0, v151
	s_nop 1
	v_cndmask_b32_e64 v147, v147, v149, s[12:13]
	v_cmp_lt_f32_e64 s[12:13], 0, v152
	s_nop 1
	v_cndmask_b32_e64 v147, v147, v150, s[12:13]
	v_mul_f32_e32 v149, 0x37800000, v147
	v_cndmask_b32_e32 v147, v147, v149, vcc
	v_cmp_class_f32_e32 vcc, v146, v234
	s_nop 1
	v_cndmask_b32_e32 v146, v147, v146, vcc
	v_div_scale_f32 v147, s[12:13], v146, v146, 1.0
	v_rcp_f32_e32 v149, v147
	v_div_scale_f32 v150, vcc, 1.0, v146, 1.0
	v_fma_f32 v151, -v147, v149, 1.0
	v_fmac_f32_e32 v149, v151, v149
	v_mul_f32_e32 v151, v150, v149
	v_fma_f32 v152, -v147, v151, v150
	v_fmac_f32_e32 v151, v152, v149
	v_fma_f32 v147, -v147, v151, v150
	v_div_fmas_f32 v147, v147, v149, v151
	v_div_fixup_f32 v146, v147, v146, 1.0
	v_lshl_add_u32 v147, v148, 2, s84
	ds_write_b32 v147, v146 offset:4096

;     __device__ __forceinline__ void operator()(const f32x4 (&acc)[2][2][4][2], const Unit& u, int wr, int wc, int fr, int fq) const {
;     ...
;         if (tid < 256) { const float* sp4 = ssq + (size_t)(u.pm * BM + tid) * 4;
;             const float t = (__hip_atomic_load(sp4, __ATOMIC_RELAXED, __HIP_MEMORY_SCOPE_AGENT) + __hip_atomic_load(sp4 + 1, __ATOMIC_RELAXED, __HIP_MEMORY_SCOPE_AGENT))
;                           + (__hip_atomic_load(sp4 + 2, __ATOMIC_RELAXED, __HIP_MEMORY_SCOPE_AGENT) + __hip_atomic_load(sp4 + 3, __ATOMIC_RELAXED, __HIP_MEMORY_SCOPE_AGENT));
;             P[1024 + tid] = 1.f / sqrtf(t * (1.f / DM) + EPS); }
.Lx10_ready:
	v_swap_b32 v151, v152
	s_mov_b32 s8, 0xf800000
	s_waitcnt vmcnt(0)
	v_pk_add_f32 v[146:147], v[150:151], v[152:153]
	s_nop 0
	v_add_f32_e32 v146, v146, v147
	v_fmamk_f32 v146, v146, 0x3a800000, v188
	v_mul_f32_e32 v147, 0x4f800000, v146
	v_cmp_gt_f32_e32 vcc, s8, v146
	s_nop 1
	v_cndmask_b32_e32 v146, v146, v147, vcc
	v_sqrt_f32_e32 v147, v146
	s_nop 0
	v_add_u32_e32 v149, -1, v147
	v_add_u32_e32 v150, 1, v147
	v_fma_f32 v151, -v149, v147, v146
	v_fma_f32 v152, -v150, v147, v146
	v_cmp_ge_f32_e64 s[12:13], 0, v151
	s_nop 1
	v_cndmask_b32_e64 v147, v147, v149, s[12:13]
	v_cmp_lt_f32_e64 s[12:13], 0, v152
	s_nop 1
	v_cndmask_b32_e64 v147, v147, v150, s[12:13]
	v_mul_f32_e32 v149, 0x37800000, v147
	v_cndmask_b32_e32 v147, v147, v149, vcc
	v_cmp_class_f32_e32 vcc, v146, v189
	s_nop 1
	v_cndmask_b32_e32 v146, v147, v146, vcc
	v_div_scale_f32 v147, s[12:13], v146, v146, 1.0
	v_rcp_f32_e32 v149, v147
	v_div_scale_f32 v150, vcc, 1.0, v146, 1.0
	v_fma_f32 v151, -v147, v149, 1.0
	v_fmac_f32_e32 v149, v151, v149
	v_mul_f32_e32 v151, v150, v149
	v_fma_f32 v152, -v147, v151, v150
	v_fmac_f32_e32 v151, v152, v149
	v_fma_f32 v147, -v147, v151, v150
	v_div_fmas_f32 v147, v147, v149, v151
	v_div_fixup_f32 v146, v147, v146, 1.0
	v_lshl_add_u32 v147, v148, 2, s84
	ds_write_b32 v147, v146 offset:4096
